# prologue: weight-transpose items of the nine matrices are dealt to rotated workgroup ranges (max 5 instead of 9 items per workgroup per layer)
# speedup vs baseline: 1.0027x; 1.0000x over previous
; #define LAS __attribute__((address_space(3)))
; __device__ __forceinline__ void transpose_matrix(const float* W, int ldw, int K, int N, int cmap, const float* gk, bf16_t* WT, LAS unsigned* img, int tid, int vb, int nvb) {
;     const int lane = tid & 63, w = tid >> 6;
;     const int nblk = N / 256, items = (K / 64) * nblk;
;     for (int it = vb; it < items; it += nvb) {
; __global__ void __launch_bounds__(512) fwd_megakernel(Params p) {
;     ...
;         for (int l = 0; l < DEPTH; ++l) {
;             unsigned char* wl = ws + WS_W + (size_t)l * W_LAYER;
;     ...
;             transpose_matrix(p.in[8] + (size_t)l * QL * NQB, NQB, QL, NQB, 0, p.in[6] + l * QL, (bf16_t*)(wl + WO_UQ), scr, tid, vcu, G);
;             transpose_matrix(p.in[9] + (size_t)l * KVL * NKVB, NKVB, KVL, NKVB, 0, p.in[7] + l * KVL, (bf16_t*)(wl + WO_UKV), scr, tid, vcu, G);
;             transpose_matrix(p.in[10] + (size_t)l * 512 * DM, DM, 512, DM, 0, nullptr, (bf16_t*)(wl + WO_A), scr, tid, vcu, G);
;             transpose_matrix(p.in[11] + (size_t)l * 512 * DM, DM, 512, DM, 0, nullptr, (bf16_t*)(wl + WO_B), scr, tid, vcu, G);
;             transpose_matrix(p.in[12] + (size_t)l * DM * DM, DM, DM, DM, 0, nullptr, (bf16_t*)(wl + WO_OUT), scr, tid, vcu, G);
;             transpose_matrix(p.in[14] + (size_t)l * DM * DFF, DFF, DM, DFF, 0, p.in[13] + l * DM, (bf16_t*)(wl + WO_FF1), scr, tid, vcu, G);
;             transpose_matrix(p.in[15] + (size_t)l * DFF * DM, DM, DFF, DM, 0, nullptr, (bf16_t*)(wl + WO_FF2), scr, tid, vcu, G);
.LBB0_7:
	s_mov_b64 s[6:7], s[84:85]
	s_and_b32 s0, s20, 0xffffffc0
	s_add_u32 s21, s6, 0x100000
	s_addc_u32 s22, s7, 0
	s_cmpk_lt_i32 s1, 0x60
	s_cselect_b64 s[10:11], -1, 0
	s_cmpk_lt_i32 s1, 0x80
	s_cselect_b64 s[14:15], -1, 0
	s_cmp_lt_i32 s1, 18
	s_cselect_b64 s[16:17], -1, 0
	s_cmp_lt_i32 s1, 16
	s_cselect_b64 s[18:19], -1, 0
	s_cmp_lt_i32 s1, 32
	s_cselect_b64 s[28:29], -1, 0
	s_cmp_lt_i32 s1, 64
	s_cselect_b64 s[30:31], -1, 0
	s_cmpk_lt_i32 s1, 0x100
	s_cselect_b64 s[34:35], -1, 0
	s_add_i32 s98, s1, 160
	s_cmp_ge_i32 s98, s86
	s_cselect_b32 s99, s86, 0
	s_sub_i32 s98, s98, s99
	s_cmp_ge_i32 s98, s86
	s_cselect_b32 s99, s86, 0
	s_sub_i32 s98, s98, s99
	v_writelane_b32 v255, s98, 1
	s_cmpk_lt_i32 s98, 128
	s_cselect_b64 s[14:15], -1, 0
	s_add_i32 s98, s1, 32
	s_cmp_ge_i32 s98, s86
	s_cselect_b32 s99, s86, 0
	s_sub_i32 s98, s98, s99
	s_cmp_ge_i32 s98, s86
	s_cselect_b32 s99, s86, 0
	s_sub_i32 s98, s98, s99
	v_writelane_b32 v255, s98, 2
	s_cmpk_lt_i32 s98, 18
	s_cselect_b64 s[16:17], -1, 0
	s_add_i32 s98, s1, 14
	s_cmp_ge_i32 s98, s86
	s_cselect_b32 s99, s86, 0
	s_sub_i32 s98, s98, s99
	s_cmp_ge_i32 s98, s86
	s_cselect_b32 s99, s86, 0
	s_sub_i32 s98, s98, s99
	v_writelane_b32 v255, s98, 3
	s_cmpk_lt_i32 s98, 16
	s_cselect_b64 s[18:19], -1, 0
	s_add_i32 s98, s1, 190
	s_cmp_ge_i32 s98, s86
	s_cselect_b32 s99, s86, 0
	s_sub_i32 s98, s98, s99
	s_cmp_ge_i32 s98, s86
	s_cselect_b32 s99, s86, 0
	s_sub_i32 s98, s98, s99
	v_writelane_b32 v255, s98, 4
	s_cmpk_lt_i32 s98, 32
	s_cselect_b64 s[28:29], -1, 0
	s_add_i32 s98, s1, 254
	s_cmp_ge_i32 s98, s86
	s_cselect_b32 s99, s86, 0
	s_sub_i32 s98, s98, s99
	s_cmp_ge_i32 s98, s86
	s_cselect_b32 s99, s86, 0
	s_sub_i32 s98, s98, s99
	v_writelane_b32 v255, s98, 5
	s_cmpk_lt_i32 s98, 64
	s_cselect_b64 s[30:31], -1, 0
	s_waitcnt lgkmcnt(0)
	s_cmp_lg_u64 s[62:63], 0
	s_cselect_b64 s[52:53], -1, 0
	s_cmp_lg_u64 s[68:69], 0
	v_writelane_b32 v252, s56, 4
	v_mbcnt_lo_u32_b32 v1, -1, 0
	v_mbcnt_hi_u32_b32 v1, -1, v1
	v_writelane_b32 v252, s57, 5
	v_writelane_b32 v252, s58, 6
	v_writelane_b32 v252, s59, 7
	v_writelane_b32 v252, s60, 8
	v_writelane_b32 v252, s61, 9
	v_writelane_b32 v252, s62, 10
	v_writelane_b32 v252, s63, 11
	v_writelane_b32 v252, s64, 12
	v_writelane_b32 v252, s65, 13
	v_writelane_b32 v252, s66, 14
	v_writelane_b32 v252, s67, 15
	v_add_u32_e32 v194, s0, v1
	v_writelane_b32 v252, s68, 16
	v_mov_b32_e32 v6, v194
	v_writelane_b32 v252, s69, 17
	v_writelane_b32 v252, s70, 18
	v_and_b32_e32 v2, 63, v6
	v_ashrrev_i32_e32 v4, 6, v6
	v_and_b32_e32 v8, 7, v6
	v_lshlrev_b32_e32 v3, 3, v4
	v_lshlrev_b32_e32 v4, 4, v4
	v_lshl_add_u32 v71, v8, 4, 0
	v_lshlrev_b32_e32 v22, 3, v8
	v_mul_u32_u24_e32 v8, 0x84, v2
	v_writelane_b32 v252, s71, 19
	v_mov_b32_e32 v5, 0
	v_add3_u32 v73, 0, v4, v8
	v_lshlrev_b32_e32 v4, 2, v2
	s_cselect_b64 s[88:89], -1, 0
	s_cmp_lg_u64 s[70:71], 0
	v_writelane_b32 v252, s1, 20
	v_lshl_add_u64 v[8:9], s[36:37], 0, v[4:5]
	v_lshl_add_u64 v[10:11], s[38:39], 0, v[4:5]
	s_cselect_b64 s[90:91], -1, 0
	v_lshl_add_u64 v[12:13], s[40:41], 0, v[4:5]
	v_lshl_add_u64 v[14:15], s[42:43], 0, v[4:5]
	v_lshl_add_u64 v[16:17], s[44:45], 0, v[4:5]
	v_lshl_add_u64 v[18:19], s[48:49], 0, v[4:5]
	s_cmp_lg_u64 s[46:47], 0
	v_lshl_add_u64 v[20:21], s[50:51], 0, v[4:5]
	v_writelane_b32 v252, s36, 21
	v_ashrrev_i32_e32 v7, 3, v6
	s_mov_b32 s9, 0
	v_writelane_b32 v252, s37, 22
	v_writelane_b32 v252, s38, 23
	v_writelane_b32 v252, s39, 24
	v_writelane_b32 v252, s40, 25
	v_writelane_b32 v252, s41, 26
	v_writelane_b32 v252, s42, 27
	v_writelane_b32 v252, s43, 28
	v_writelane_b32 v252, s44, 29
	v_writelane_b32 v252, s45, 30
	v_writelane_b32 v252, s46, 31
	v_writelane_b32 v252, s47, 32
	v_writelane_b32 v252, s48, 33
	v_writelane_b32 v252, s49, 34
	s_movk_i32 s0, 0x84
	v_add_u32_e32 v23, 0xc0, v7
	v_writelane_b32 v252, s50, 35
	v_mul_lo_u32 v72, v7, s0
	s_cselect_b64 s[92:93], -1, 0
	s_movk_i32 s23, 0x5a0
	s_movk_i32 s24, 0x3680
	s_mov_b64 s[94:95], 0x300000
	s_mov_b64 s[96:97], 0x700000
	s_movk_i32 s25, 0xc00
	s_movk_i32 s26, 0x300
	v_lshlrev_b32_e32 v4, 2, v2
	v_lshlrev_b32_e32 v22, 1, v22
	v_lshl_add_u32 v74, s1, 8, v23
	v_mov_b32_e32 v75, 0x120000
	s_mov_b64 s[4:5], 0x800000
	s_mov_b64 s[12:13], 0x900000
	s_mov_b64 s[54:55], 0xa00000
	s_mov_b64 s[56:57], 0xb00000
	s_mov_b64 s[58:59], 0xd00000
	s_mov_b64 s[60:61], 0x1500000
	s_mov_b32 s62, s9
	v_writelane_b32 v252, s51, 36
	s_branch .LBB0_9

; __device__ __forceinline__ void transpose_matrix(const float* W, int ldw, int K, int N, int cmap, const float* gk, bf16_t* WT, LAS unsigned* img, int tid, int vb, int nvb) {
;     ...
;     for (int it = vb; it < items; it += nvb) {
;         const int kb = it / nblk, nb = it % nblk, n0 = nb * 256, k0 = kb * 64 + w * 8;
.LBB0_92:
	v_readlane_b32 s36, v252, 21
	s_andn2_b64 vcc, exec, s[14:15]
	v_readlane_b32 s46, v252, 31
	v_readlane_b32 s47, v252, 32
	v_readlane_b32 s37, v252, 22
	v_readlane_b32 s38, v252, 23
	v_readlane_b32 s39, v252, 24
	v_readlane_b32 s40, v252, 25
	v_readlane_b32 s41, v252, 26
	v_readlane_b32 s42, v252, 27
	v_readlane_b32 s43, v252, 28
	v_readlane_b32 s44, v252, 29
	v_readlane_b32 s45, v252, 30
	v_readlane_b32 s48, v252, 33
	v_readlane_b32 s49, v252, 34
	v_readlane_b32 s50, v252, 35
	v_readlane_b32 s51, v252, 36
	s_cbranch_vccnz .LBB0_111
	v_mov_b32_e32 v23, v5
	v_readlane_b32 s72, v255, 1
	v_readlane_b32 s98, v252, 20
	s_nop 0
	s_sub_i32 s98, s72, s98
	s_lshl_b32 s98, s98, 8
	v_lshl_add_u64 v[26:27], s[64:65], 0, v[22:23]
	s_lshl_b32 s0, s72, 7
	v_lshl_add_u64 v[24:25], s[70:71], 0, v[4:5]
	v_lshl_add_u64 v[26:27], v[26:27], 0, s[94:95]
	s_lshl_b32 s27, s86, 8
	s_add_i32 s33, s0, 0x9a0
	s_lshl_b32 s63, s86, 7
	v_add_u32_e32 v23, s98, v74
	s_branch .LBB0_95

; __device__ __forceinline__ void transpose_matrix(const float* W, int ldw, int K, int N, int cmap, const float* gk, bf16_t* WT, LAS unsigned* img, int tid, int vb, int nvb) {
;     ...
;     for (int it = vb; it < items; it += nvb) {
;         const int kb = it / nblk, nb = it % nblk, n0 = nb * 256, k0 = kb * 64 + w * 8;
; __global__ void __launch_bounds__(512) fwd_megakernel(Params p) {
;     ...
;             transpose_matrix(p.in[8] + (size_t)l * QL * NQB, NQB, QL, NQB, 0, p.in[6] + l * QL, (bf16_t*)(wl + WO_UQ), scr, tid, vcu, G);
.LBB0_114:
	s_mul_i32 s8, s62, 0x180
	v_readlane_b32 s36, v252, 4
	s_lshl_b64 s[0:1], s[8:9], 2
	v_readlane_b32 s48, v252, 16
	v_mov_b32_e32 v23, v5
	v_readlane_b32 s49, v252, 17
	s_add_u32 s68, s48, s0
	v_lshl_add_u64 v[26:27], s[64:65], 0, v[22:23]
	v_readlane_b32 s33, v255, 2
	s_addc_u32 s69, s49, s1
	v_mad_u64_u32 v[24:25], s[0:1], s62, v75, v[8:9]
	v_lshl_add_u64 v[26:27], v[26:27], 0, s[96:97]
	s_lshl_b32 s8, s33, 8
	s_lshl_b32 s27, s86, 8
	v_readlane_b32 s37, v252, 5
	v_readlane_b32 s38, v252, 6
	v_readlane_b32 s39, v252, 7
	v_readlane_b32 s40, v252, 8
	v_readlane_b32 s41, v252, 9
	v_readlane_b32 s42, v252, 10
	v_readlane_b32 s43, v252, 11
	v_readlane_b32 s44, v252, 12
	v_readlane_b32 s45, v252, 13
	v_readlane_b32 s46, v252, 14
	v_readlane_b32 s47, v252, 15
	v_readlane_b32 s50, v252, 18
	v_readlane_b32 s51, v252, 19
	s_branch .LBB0_116

; __device__ __forceinline__ void transpose_matrix(const float* W, int ldw, int K, int N, int cmap, const float* gk, bf16_t* WT, LAS unsigned* img, int tid, int vb, int nvb) {
;     ...
;     for (int it = vb; it < items; it += nvb) {
;         const int kb = it / nblk, nb = it % nblk, n0 = nb * 256, k0 = kb * 64 + w * 8;
; __global__ void __launch_bounds__(512) fwd_megakernel(Params p) {
;     ...
;             transpose_matrix(p.in[9] + (size_t)l * KVL * NKVB, NKVB, KVL, NKVB, 0, p.in[7] + l * KVL, (bf16_t*)(wl + WO_UKV), scr, tid, vcu, G);
.LBB0_133:
	s_lshl_b32 s8, s62, 8
	v_readlane_b32 s36, v252, 4
	s_lshl_b64 s[0:1], s[8:9], 2
	v_readlane_b32 s50, v252, 18
	v_readlane_b32 s51, v252, 19
	s_add_u32 s68, s50, s0
	v_mov_b32_e32 v23, v5
	s_addc_u32 s69, s51, s1
	s_lshl_b64 s[0:1], s[62:63], 20
	v_lshl_add_u64 v[26:27], s[64:65], 0, v[22:23]
	v_readlane_b32 s33, v255, 3
	v_lshl_add_u64 v[24:25], v[10:11], 0, s[0:1]
	v_lshl_add_u64 v[26:27], v[26:27], 0, s[4:5]
	s_lshl_b32 s8, s33, 8
	s_lshl_b32 s27, s86, 8
	v_readlane_b32 s37, v252, 5
	v_readlane_b32 s38, v252, 6
	v_readlane_b32 s39, v252, 7
	v_readlane_b32 s40, v252, 8
	v_readlane_b32 s41, v252, 9
	v_readlane_b32 s42, v252, 10
	v_readlane_b32 s43, v252, 11
	v_readlane_b32 s44, v252, 12
	v_readlane_b32 s45, v252, 13
	v_readlane_b32 s46, v252, 14
	v_readlane_b32 s47, v252, 15
	v_readlane_b32 s48, v252, 16
	v_readlane_b32 s49, v252, 17
	s_branch .LBB0_135

; __device__ __forceinline__ unsigned pk_bf16(float lo, float hi) { typedef float f2_t __attribute__((ext_vector_type(2))); typedef __bf16 b2_t __attribute__((ext_vector_type(2))); f2_t v = {lo, hi}; b2_t b = __builtin_convertvector(v, b2_t); return __builtin_bit_cast(unsigned, b); }
; #define LAS __attribute__((address_space(3)))
; __device__ __forceinline__ void transpose_matrix(const float* W, int ldw, int K, int N, int cmap, const float* gk, bf16_t* WT, LAS unsigned* img, int tid, int vb, int nvb) {
;     ...
;     for (int it = vb; it < items; it += nvb) {
;         const int kb = it / nblk, nb = it % nblk, n0 = nb * 256, k0 = kb * 64 + w * 8;
;         float v[4][4][2];
; #pragma unroll
;         for (int j = 0; j < 4; ++j) {
;             const int nn = n0 + 64 * j;
;             int c0 = nn;
;             if (cmap == 1) c0 = nn; else if (cmap == 2) c0 = 1440 + ((nn & 255) >> 7) * 1024 + (nn >> 8) * 128 + (nn & 127);
;             const bool ok = (cmap != 1) || (nn + lane < 1440);
; #pragma unroll
;             for (int kp = 0; kp < 4; ++kp)
; #pragma unroll
;                 for (int e = 0; e < 2; ++e) v[j][kp][e] = ok ? W[(size_t)(k0 + 2 * kp + e) * ldw + c0 + lane] : 0.f;
;         }
;         float g[8];
; #pragma unroll
;         for (int i = 0; i < 8; ++i) g[i] = gk ? gk[k0 + i] : 1.f;
;         __syncthreads();
; #pragma unroll
;         for (int j = 0; j < 4; ++j)
; #pragma unroll
;             for (int kp = 0; kp < 4; ++kp) img[(64 * j + lane) * 33 + w * 4 + kp] = pk_bf16(v[j][kp][0] * g[2 * kp], v[j][kp][1] * g[2 * kp + 1]);
;         __syncthreads();
; #pragma unroll
;         for (int i = 0; i < 4; ++i) {
;             const int n = (tid >> 3) + 64 * i, c = tid & 7;
;             const LAS unsigned* q = img + n * 33 + c * 4;
;             u32x4 o; o.x = q[0]; o.y = q[1]; o.z = q[2]; o.w = q[3];
;             *(u32x4*)(WT + (size_t)(n0 + n) * K + kb * 64 + c * 8) = o;
;         }
.LBB0_152:
	v_mov_b32_e32 v23, v5
	v_readlane_b32 s72, v255, 4
	s_lshl_b64 s[68:69], s[62:63], 21
	v_lshl_add_u64 v[26:27], s[64:65], 0, v[22:23]
	s_lshl_b32 s8, s72, 8
	s_lshl_b64 s[0:1], s[62:63], 19
	v_lshl_add_u64 v[24:25], v[12:13], 0, s[68:69]
	v_lshl_add_u64 v[26:27], v[26:27], 0, s[12:13]
	s_lshl_b32 s27, s86, 8
	s_mov_b32 s33, s8
.LBB0_153:
	s_ashr_i32 s68, s72, 31
	s_lshr_b32 s68, s68, 30
	s_add_i32 s68, s72, s68
	s_ashr_i32 s68, s68, 2
	s_lshl_b32 s70, s68, 6
	s_lshl_b32 s69, s68, 10
	v_add_u32_e32 v28, s70, v3
	s_sub_i32 s68, s33, s69
	v_or_b32_e32 v40, 6, v28
	s_ashr_i32 s69, s68, 31
	v_ashrrev_i32_e32 v29, 31, v28
	v_or_b32_e32 v30, 1, v28
	v_or_b32_e32 v32, 2, v28
	v_or_b32_e32 v34, 3, v28
	v_or_b32_e32 v36, 4, v28
	v_or_b32_e32 v38, 5, v28
	v_or_b32_e32 v42, 7, v28
	v_ashrrev_i32_e32 v41, 31, v40
	v_lshl_add_u64 v[44:45], s[68:69], 2, v[24:25]
	v_lshlrev_b64 v[28:29], 12, v[28:29]
	v_ashrrev_i32_e32 v31, 31, v30
	v_ashrrev_i32_e32 v33, 31, v32
	v_ashrrev_i32_e32 v35, 31, v34
	v_ashrrev_i32_e32 v37, 31, v36
	v_ashrrev_i32_e32 v39, 31, v38
	v_ashrrev_i32_e32 v43, 31, v42
	v_lshlrev_b64 v[40:41], 12, v[40:41]
	v_lshl_add_u64 v[28:29], v[44:45], 0, v[28:29]
	v_lshlrev_b64 v[30:31], 12, v[30:31]
	v_lshlrev_b64 v[32:33], 12, v[32:33]
	v_lshlrev_b64 v[34:35], 12, v[34:35]
	v_lshlrev_b64 v[36:37], 12, v[36:37]
	v_lshlrev_b64 v[38:39], 12, v[38:39]
	v_lshlrev_b64 v[42:43], 12, v[42:43]
	v_lshl_add_u64 v[40:41], v[44:45], 0, v[40:41]
	v_lshl_add_u64 v[30:31], v[44:45], 0, v[30:31]
	v_lshl_add_u64 v[32:33], v[44:45], 0, v[32:33]
	v_lshl_add_u64 v[34:35], v[44:45], 0, v[34:35]
	v_lshl_add_u64 v[36:37], v[44:45], 0, v[36:37]
	v_lshl_add_u64 v[38:39], v[44:45], 0, v[38:39]
	v_lshl_add_u64 v[42:43], v[44:45], 0, v[42:43]
	global_load_dword v23, v[28:29], off
	global_load_dword v50, v[28:29], off offset:256
	global_load_dword v51, v[28:29], off offset:512
	global_load_dword v52, v[30:31], off
	global_load_dword v53, v[32:33], off
	global_load_dword v54, v[34:35], off
	global_load_dword v55, v[32:33], off offset:256
	global_load_dword v56, v[34:35], off offset:256
	global_load_dword v57, v[36:37], off
	global_load_dword v68, v[38:39], off
	global_load_dword v69, v[36:37], off offset:256
	global_load_dword v76, v[38:39], off offset:256
	global_load_dword v77, v[36:37], off offset:512
	global_load_dword v78, v[38:39], off offset:512
	global_load_dword v79, v[40:41], off
	global_load_dword v80, v[42:43], off
	global_load_dword v81, v[40:41], off offset:256
	global_load_dword v82, v[42:43], off offset:256
	global_load_dword v83, v[40:41], off offset:512
	global_load_dword v84, v[42:43], off offset:512
	global_load_dword v85, v[30:31], off offset:256
	global_load_dword v86, v[30:31], off offset:512
	global_load_dword v87, v[30:31], off offset:768
	global_load_dword v88, v[28:29], off offset:768
	global_load_dword v89, v[32:33], off offset:512
	global_load_dword v90, v[34:35], off offset:512
	global_load_dword v91, v[34:35], off offset:768
	global_load_dword v92, v[32:33], off offset:768
	global_load_dword v93, v[38:39], off offset:768
	global_load_dword v94, v[36:37], off offset:768
	global_load_dword v95, v[42:43], off offset:768
	s_nop 0
	global_load_dword v41, v[40:41], off offset:768
	v_add_u32_e32 v42, s68, v7
	s_ashr_i32 s71, s70, 31
	v_ashrrev_i32_e32 v43, 31, v42
	v_add_u32_e32 v44, 64, v42
	v_add_u32_e32 v46, 0x80, v42
	v_lshl_add_u64 v[58:59], s[70:71], 1, v[26:27]
	v_add_u32_e32 v48, 0xc0, v42
	v_lshlrev_b64 v[42:43], 10, v[42:43]
	v_ashrrev_i32_e32 v45, 31, v44
	v_ashrrev_i32_e32 v47, 31, v46
	v_ashrrev_i32_e32 v49, 31, v48
	v_lshl_add_u64 v[60:61], v[58:59], 0, v[42:43]
	v_lshlrev_b64 v[42:43], 10, v[44:45]
	v_lshlrev_b64 v[44:45], 10, v[46:47]
	v_add_u32_e32 v34, v71, v72
	v_lshlrev_b64 v[62:63], 10, v[48:49]
	v_lshl_add_u64 v[64:65], v[58:59], 0, v[42:43]
	v_lshl_add_u64 v[66:67], v[58:59], 0, v[44:45]
	v_add_u32_e32 v28, 0x2100, v73
	v_add_u32_e32 v29, 0x2108, v73
	v_add_u32_e32 v30, 0x4200, v73
	v_add_u32_e32 v31, 0x4208, v73
	v_add_u32_e32 v32, 0x6300, v73
	v_add_u32_e32 v33, 0x6308, v73
	v_add_u32_e32 v35, 0x2100, v34
	v_add_u32_e32 v36, 0x2108, v34
	v_add_u32_e32 v37, 0x4200, v34
	v_add_u32_e32 v38, 0x4208, v34
	v_add_u32_e32 v39, 0x6300, v34
	v_add_u32_e32 v40, 0x6308, v34
	s_barrier
	s_add_i32 s72, s72, s86
	s_add_i32 s33, s33, s27
	s_cmp_lt_i32 s72, 32
	v_lshl_add_u64 v[58:59], v[58:59], 0, v[62:63]
	s_waitcnt vmcnt(28)
	v_cvt_pk_bf16_f32 v23, v23, v52
	s_waitcnt vmcnt(26)
	v_cvt_pk_bf16_f32 v42, v53, v54
	s_waitcnt vmcnt(24)
	v_cvt_pk_bf16_f32 v46, v55, v56
	s_waitcnt vmcnt(22)
	v_cvt_pk_bf16_f32 v43, v57, v68
	s_waitcnt vmcnt(20)
	v_cvt_pk_bf16_f32 v47, v69, v76
	s_waitcnt vmcnt(16)
	v_cvt_pk_bf16_f32 v44, v79, v80
	s_waitcnt vmcnt(14)
	v_cvt_pk_bf16_f32 v48, v81, v82
	s_waitcnt vmcnt(12)
	v_cvt_pk_bf16_f32 v52, v83, v84
	s_waitcnt vmcnt(11)
	v_cvt_pk_bf16_f32 v45, v50, v85
	s_waitcnt vmcnt(10)
	v_cvt_pk_bf16_f32 v49, v51, v86
	v_cvt_pk_bf16_f32 v51, v77, v78
	s_waitcnt vmcnt(8)
	v_cvt_pk_bf16_f32 v53, v88, v87
	s_waitcnt vmcnt(6)
	v_cvt_pk_bf16_f32 v50, v89, v90
	s_waitcnt vmcnt(4)
	v_cvt_pk_bf16_f32 v54, v92, v91
	s_waitcnt vmcnt(2)
	v_cvt_pk_bf16_f32 v55, v94, v93
	s_waitcnt vmcnt(0)
	v_cvt_pk_bf16_f32 v41, v41, v95
	ds_write2_b32 v73, v23, v42 offset1:1
	ds_write2_b32 v73, v43, v44 offset0:2 offset1:3
	ds_write2_b32 v28, v45, v46 offset1:1
	ds_write2_b32 v29, v47, v48 offset1:1
	ds_write2_b32 v30, v49, v50 offset1:1
	ds_write2_b32 v31, v51, v52 offset1:1
	ds_write2_b32 v32, v53, v54 offset1:1
	ds_write2_b32 v33, v55, v41 offset1:1
	s_waitcnt lgkmcnt(0)
	s_barrier
	ds_read2_b32 v[42:43], v34 offset1:1
	ds_read2_b32 v[44:45], v34 offset0:2 offset1:3
	ds_read2_b32 v[46:47], v35 offset1:1
	ds_read2_b32 v[48:49], v36 offset1:1
	ds_read2_b32 v[50:51], v37 offset1:1
	ds_read2_b32 v[52:53], v38 offset1:1
	ds_read2_b32 v[54:55], v39 offset1:1
	ds_read2_b32 v[56:57], v40 offset1:1
	s_waitcnt lgkmcnt(6)
	global_store_dwordx4 v[60:61], v[42:45], off
	s_waitcnt lgkmcnt(4)
	global_store_dwordx4 v[64:65], v[46:49], off
	s_waitcnt lgkmcnt(2)
	global_store_dwordx4 v[66:67], v[50:53], off
	s_waitcnt lgkmcnt(0)
	global_store_dwordx4 v[58:59], v[54:57], off
	s_cbranch_scc1 .LBB0_153
	v_mov_b32_e32 v23, v5
	v_lshl_add_u64 v[26:27], s[64:65], 0, v[22:23]
	v_lshl_add_u64 v[24:25], s[0:1], 2, v[14:15]
	v_lshl_add_u64 v[26:27], v[26:27], 0, s[54:55]
	v_readlane_b32 s33, v255, 4

; __device__ __forceinline__ void transpose_matrix(const float* W, int ldw, int K, int N, int cmap, const float* gk, bf16_t* WT, LAS unsigned* img, int tid, int vb, int nvb) {
;     ...
;     for (int it = vb; it < items; it += nvb) {
;         const int kb = it / nblk, nb = it % nblk, n0 = nb * 256, k0 = kb * 64 + w * 8;
; __global__ void __launch_bounds__(512) fwd_megakernel(Params p) {
;     ...
;             transpose_matrix(p.in[12] + (size_t)l * DM * DM, DM, DM, DM, 0, nullptr, (bf16_t*)(wl + WO_OUT), scr, tid, vcu, G);
.LBB0_156:
	s_andn2_b64 vcc, exec, s[30:31]
	s_cbranch_vccnz .LBB0_159
	v_mov_b32_e32 v23, v5
	s_lshl_b64 s[0:1], s[62:63], 22
	v_lshl_add_u64 v[26:27], s[64:65], 0, v[22:23]
	v_readlane_b32 s33, v255, 5
	v_lshl_add_u64 v[24:25], v[16:17], 0, s[0:1]
	v_lshl_add_u64 v[26:27], v[26:27], 0, s[56:57]
	s_lshl_b32 s8, s33, 8
	s_lshl_b32 s27, s86, 8
